# v27 variant: priority 3 kept from the K-step DMA issue through the first fragment reads (no reset to 0 before them)
# speedup vs baseline: 1.0193x; 1.0041x over previous
.LBB0_303:
	s_setprio 3
	s_and_b32 s1, s0, 0x2000
	s_xor_b32 s8, s1, 0x2000
	s_lshl_b32 s101, s8, 1
	s_add_u32 s101, s101, s100
	s_add_u32 m0, s101, 0x0
	s_nop 0
	global_load_lds_dwordx4 v[184:185], off
	s_add_u32 m0, s101, 0x1000
	v_lshl_add_u64 v[184:185], v[184:185], 0, vcc
	global_load_lds_dwordx4 v[186:187], off
	s_add_u32 m0, s101, 0x2000
	v_lshl_add_u64 v[186:187], v[186:187], 0, vcc
	global_load_lds_dwordx4 v[188:189], off
	s_add_u32 m0, s101, 0x3000
	v_lshl_add_u64 v[188:189], v[188:189], 0, vcc
	global_load_lds_dwordx4 v[190:191], off
	s_add_u32 m0, s101, 0x8000
	v_lshl_add_u64 v[190:191], v[190:191], 0, vcc
	global_load_lds_dwordx4 v[192:193], off
	s_add_u32 m0, s101, 0x9000
	v_lshl_add_u64 v[192:193], v[192:193], 0, vcc
	global_load_lds_dwordx4 v[194:195], off
	s_add_u32 m0, s101, 0xa000
	v_lshl_add_u64 v[194:195], v[194:195], 0, vcc
	global_load_lds_dwordx4 v[196:197], off
	s_add_u32 m0, s101, 0xb000
	v_lshl_add_u64 v[196:197], v[196:197], 0, vcc
	global_load_lds_dwordx4 v[198:199], off
	v_lshl_add_u64 v[198:199], v[198:199], 0, vcc
	s_lshl_b32 s1, s1, 1
	v_add_u32_e32 v82, s1, v86
	v_add_u32_e32 v83, s1, v85
	v_add_u32_e32 v95, v82, v93
	ds_read_b128 v[96:99], v95
	ds_read_b128 v[100:103], v95 offset:2048
	ds_read_b128 v[120:123], v95 offset:4096
	ds_read_b128 v[124:127], v95 offset:6144
	v_add_u32_e32 v95, v83, v93
	ds_read_b128 v[128:131], v95 offset:32768
	ds_read_b128 v[132:135], v95 offset:34816
	ds_read_b128 v[136:139], v95 offset:36864
	ds_read_b128 v[140:143], v95 offset:38912
	s_setprio 1
	s_waitcnt lgkmcnt(0)
	v_mfma_f32_16x16x32_bf16 v[60:63], v[128:131], v[96:99], v[60:63]
	v_mfma_f32_16x16x32_bf16 v[56:59], v[132:135], v[96:99], v[56:59]
	v_mfma_f32_16x16x32_bf16 v[52:55], v[136:139], v[96:99], v[52:55]
	v_mfma_f32_16x16x32_bf16 v[48:51], v[140:143], v[96:99], v[48:51]
	v_mfma_f32_16x16x32_bf16 v[44:47], v[128:131], v[100:103], v[44:47]
	v_mfma_f32_16x16x32_bf16 v[40:43], v[132:135], v[100:103], v[40:43]
	v_mfma_f32_16x16x32_bf16 v[36:39], v[136:139], v[100:103], v[36:39]
	v_mfma_f32_16x16x32_bf16 v[32:35], v[140:143], v[100:103], v[32:35]
	v_mfma_f32_16x16x32_bf16 v[28:31], v[128:131], v[120:123], v[28:31]
	v_mfma_f32_16x16x32_bf16 v[24:27], v[132:135], v[120:123], v[24:27]
	v_mfma_f32_16x16x32_bf16 v[20:23], v[136:139], v[120:123], v[20:23]
	v_mfma_f32_16x16x32_bf16 v[16:19], v[140:143], v[120:123], v[16:19]
	v_mfma_f32_16x16x32_bf16 v[12:15], v[128:131], v[124:127], v[12:15]
	v_mfma_f32_16x16x32_bf16 v[8:11], v[132:135], v[124:127], v[8:11]
	v_mfma_f32_16x16x32_bf16 v[4:7], v[136:139], v[124:127], v[4:7]
	v_mfma_f32_16x16x32_bf16 v[0:3], v[140:143], v[124:127], v[0:3]
	s_setprio 0
	v_add_u32_e32 v82, v82, v94
	ds_read_b128 v[96:99], v82
	ds_read_b128 v[100:103], v82 offset:2048
	ds_read_b128 v[120:123], v82 offset:4096
	ds_read_b128 v[124:127], v82 offset:6144
	v_add_u32_e32 v82, v83, v94
	ds_read_b128 v[128:131], v82 offset:32768
	ds_read_b128 v[132:135], v82 offset:34816
	ds_read_b128 v[136:139], v82 offset:36864
	ds_read_b128 v[140:143], v82 offset:38912
	s_setprio 1
	s_waitcnt lgkmcnt(0)
	v_mfma_f32_16x16x32_bf16 v[60:63], v[128:131], v[96:99], v[60:63]
	v_mfma_f32_16x16x32_bf16 v[56:59], v[132:135], v[96:99], v[56:59]
	v_mfma_f32_16x16x32_bf16 v[52:55], v[136:139], v[96:99], v[52:55]
	v_mfma_f32_16x16x32_bf16 v[48:51], v[140:143], v[96:99], v[48:51]
	v_mfma_f32_16x16x32_bf16 v[44:47], v[128:131], v[100:103], v[44:47]
	v_mfma_f32_16x16x32_bf16 v[40:43], v[132:135], v[100:103], v[40:43]
	v_mfma_f32_16x16x32_bf16 v[36:39], v[136:139], v[100:103], v[36:39]
	v_mfma_f32_16x16x32_bf16 v[32:35], v[140:143], v[100:103], v[32:35]
	v_mfma_f32_16x16x32_bf16 v[28:31], v[128:131], v[120:123], v[28:31]
	v_mfma_f32_16x16x32_bf16 v[24:27], v[132:135], v[120:123], v[24:27]
	v_mfma_f32_16x16x32_bf16 v[20:23], v[136:139], v[120:123], v[20:23]
	v_mfma_f32_16x16x32_bf16 v[16:19], v[140:143], v[120:123], v[16:19]
	v_mfma_f32_16x16x32_bf16 v[12:15], v[128:131], v[124:127], v[12:15]
	v_mfma_f32_16x16x32_bf16 v[8:11], v[132:135], v[124:127], v[8:11]
	v_mfma_f32_16x16x32_bf16 v[4:7], v[136:139], v[124:127], v[4:7]
	v_mfma_f32_16x16x32_bf16 v[0:3], v[140:143], v[124:127], v[0:3]
	s_setprio 0
	s_addk_i32 s0, 0x2000
	s_waitcnt vmcnt(0)
	s_add_u32 s20, s20, 0x80
	s_addc_u32 s21, s21, 0
	s_cmpk_lg_i32 s20, 0x780
	s_waitcnt vmcnt(0)
	s_barrier
	s_cbranch_scc1 .LBB0_303
	ds_read_b128 v[78:81], v89 offset:55296
	ds_read_b128 v[96:99], v89 offset:53248
	ds_read_b128 v[100:103], v89 offset:51200
	ds_read_b128 v[120:123], v89 offset:49152
	ds_read_b128 v[124:127], v90 offset:22528
	ds_read_b128 v[128:131], v90 offset:20480
	ds_read_b128 v[132:135], v90 offset:18432
	ds_read_b128 v[136:139], v90 offset:16384
	s_setprio 1
	s_waitcnt lgkmcnt(0)
	v_mfma_f32_16x16x32_bf16 v[60:63], v[120:123], v[136:139], v[60:63]
	v_mfma_f32_16x16x32_bf16 v[56:59], v[100:103], v[136:139], v[56:59]
	v_mfma_f32_16x16x32_bf16 v[52:55], v[96:99], v[136:139], v[52:55]
	v_mfma_f32_16x16x32_bf16 v[48:51], v[78:81], v[136:139], v[48:51]
	v_mfma_f32_16x16x32_bf16 v[44:47], v[120:123], v[132:135], v[44:47]
	v_mfma_f32_16x16x32_bf16 v[40:43], v[100:103], v[132:135], v[40:43]
	v_mfma_f32_16x16x32_bf16 v[36:39], v[96:99], v[132:135], v[36:39]
	v_mfma_f32_16x16x32_bf16 v[32:35], v[78:81], v[132:135], v[32:35]
	v_mfma_f32_16x16x32_bf16 v[28:31], v[120:123], v[128:131], v[28:31]
	v_mfma_f32_16x16x32_bf16 v[24:27], v[100:103], v[128:131], v[24:27]
	v_mfma_f32_16x16x32_bf16 v[20:23], v[96:99], v[128:131], v[20:23]
	v_mfma_f32_16x16x32_bf16 v[16:19], v[78:81], v[128:131], v[16:19]
	v_mfma_f32_16x16x32_bf16 v[12:15], v[120:123], v[124:127], v[12:15]
	v_mfma_f32_16x16x32_bf16 v[8:11], v[100:103], v[124:127], v[8:11]
	v_mfma_f32_16x16x32_bf16 v[4:7], v[96:99], v[124:127], v[4:7]
	v_mfma_f32_16x16x32_bf16 v[0:3], v[78:81], v[124:127], v[0:3]
	s_setprio 0
	ds_read_b128 v[78:81], v91 offset:16384
	ds_read_b128 v[96:99], v91 offset:18432
	ds_read_b128 v[100:103], v91 offset:20480
	ds_read_b128 v[120:123], v91 offset:22528
	ds_read_b128 v[124:127], v92 offset:49152
	ds_read_b128 v[128:131], v92 offset:51200
	ds_read_b128 v[132:135], v92 offset:53248
	ds_read_b128 v[136:139], v92 offset:55296
	s_setprio 1
	s_waitcnt lgkmcnt(3)
	v_mfma_f32_16x16x32_bf16 v[60:63], v[124:127], v[78:81], v[60:63]
	s_waitcnt lgkmcnt(2)
	v_mfma_f32_16x16x32_bf16 v[56:59], v[128:131], v[78:81], v[56:59]
	s_waitcnt lgkmcnt(1)
	v_mfma_f32_16x16x32_bf16 v[52:55], v[132:135], v[78:81], v[52:55]
	s_waitcnt lgkmcnt(0)
	v_mfma_f32_16x16x32_bf16 v[48:51], v[136:139], v[78:81], v[48:51]
	v_mfma_f32_16x16x32_bf16 v[44:47], v[124:127], v[96:99], v[44:47]
	v_mfma_f32_16x16x32_bf16 v[40:43], v[128:131], v[96:99], v[40:43]
	v_mfma_f32_16x16x32_bf16 v[36:39], v[132:135], v[96:99], v[36:39]
	v_mfma_f32_16x16x32_bf16 v[32:35], v[136:139], v[96:99], v[32:35]
	v_mfma_f32_16x16x32_bf16 v[28:31], v[124:127], v[100:103], v[28:31]
	v_mfma_f32_16x16x32_bf16 v[24:27], v[128:131], v[100:103], v[24:27]
	v_mfma_f32_16x16x32_bf16 v[20:23], v[132:135], v[100:103], v[20:23]
	v_mfma_f32_16x16x32_bf16 v[16:19], v[136:139], v[100:103], v[16:19]
	v_mfma_f32_16x16x32_bf16 v[12:15], v[124:127], v[120:123], v[12:15]
	v_mfma_f32_16x16x32_bf16 v[8:11], v[128:131], v[120:123], v[8:11]
	v_mfma_f32_16x16x32_bf16 v[4:7], v[132:135], v[120:123], v[4:7]
	v_mfma_f32_16x16x32_bf16 v[0:3], v[136:139], v[120:123], v[0:3]
	s_setprio 0
	s_waitcnt vmcnt(0)
	s_cmp_lt_i32 s10, 32
	s_mov_b64 s[0:1], -1
	s_barrier
	s_cbranch_scc1 .LBB0_594
	s_cmp_eq_u32 s10, 32
	s_cselect_b64 s[0:1], -1, 0
	s_and_b64 vcc, exec, s[0:1]
	v_mov_b32_e32 v79, v63
	v_mov_b32_e32 v82, v62
	v_mov_b32_e32 v83, v61
	v_mov_b32_e32 v95, v60
	s_cbranch_vccz .LBB0_323
	v_cmp_nlt_f32_e64 s[8:9], |v60|, s33
	s_and_saveexec_b64 s[12:13], s[8:9]
	s_xor_b64 s[8:9], exec, s[12:13]
	s_cbranch_execz .LBB0_308
	v_add_f32_e64 v78, |v60|, |v60|
	v_mul_f32_e32 v79, 0x3fb8aa3b, v78
	v_rndne_f32_e32 v80, v79
	s_mov_b32 s11, 0x3fb8aa3b
	v_sub_f32_e32 v81, v79, v80
	v_fma_f32 v79, v78, s11, -v79
	v_fmac_f32_e32 v79, 0x32a5705f, v78
	v_add_f32_e32 v79, v81, v79
	v_cvt_i32_f32_e32 v80, v80
	v_exp_f32_e32 v79, v79
	s_mov_b32 s11, 0xc2ce8ed0
	v_cmp_ngt_f32_e32 vcc, s11, v78
	s_mov_b32 s11, 0x42b17218
	v_ldexp_f32 v79, v79, v80
	v_cndmask_b32_e32 v79, 0, v79, vcc
	v_cmp_nlt_f32_e32 vcc, s11, v78
	s_nop 1
	v_cndmask_b32_e32 v78, v112, v79, vcc
	v_add_f32_e32 v78, 1.0, v78
	v_rcp_f32_e32 v78, v78
	s_nop 0
	v_fma_f32 v78, v78, -2.0, 1.0

.LBB0_882:
	s_setprio 3
	s_and_b32 s6, s0, 0x2000
	s_xor_b32 s8, s6, 0x2000
	s_lshl_b32 s101, s8, 1
	s_add_u32 s101, s101, s100
	s_add_u32 m0, s101, 0x0
	s_nop 0
	global_load_lds_dwordx4 v[184:185], off
	s_add_u32 m0, s101, 0x1000
	v_lshl_add_u64 v[184:185], v[184:185], 0, vcc
	global_load_lds_dwordx4 v[186:187], off
	s_add_u32 m0, s101, 0x2000
	v_lshl_add_u64 v[186:187], v[186:187], 0, vcc
	global_load_lds_dwordx4 v[188:189], off
	s_add_u32 m0, s101, 0x3000
	v_lshl_add_u64 v[188:189], v[188:189], 0, vcc
	global_load_lds_dwordx4 v[190:191], off
	s_add_u32 m0, s101, 0x8000
	v_lshl_add_u64 v[190:191], v[190:191], 0, vcc
	global_load_lds_dwordx4 v[192:193], off
	s_add_u32 m0, s101, 0x9000
	v_lshl_add_u64 v[192:193], v[192:193], 0, vcc
	global_load_lds_dwordx4 v[194:195], off
	s_add_u32 m0, s101, 0xa000
	v_lshl_add_u64 v[194:195], v[194:195], 0, vcc
	global_load_lds_dwordx4 v[196:197], off
	s_add_u32 m0, s101, 0xb000
	v_lshl_add_u64 v[196:197], v[196:197], 0, vcc
	global_load_lds_dwordx4 v[198:199], off
	v_lshl_add_u64 v[198:199], v[198:199], 0, vcc
	s_lshl_b32 s6, s6, 1
	v_add_u32_e32 v102, s6, v90
	v_add_u32_e32 v103, s6, v71
	v_add_u32_e32 v128, v102, v96
	v_add_u32_e32 v144, v103, v96
	ds_read_b128 v[98:101], v128
	ds_read_b128 v[120:123], v128 offset:2048
	ds_read_b128 v[124:127], v128 offset:4096
	ds_read_b128 v[128:131], v128 offset:6144
	ds_read_b128 v[132:135], v144 offset:32768
	ds_read_b128 v[136:139], v144 offset:34816
	ds_read_b128 v[140:143], v144 offset:36864
	ds_read_b128 v[144:147], v144 offset:38912
	s_setprio 1
	s_waitcnt lgkmcnt(0)
	v_mfma_f32_16x16x32_bf16 v[60:63], v[132:135], v[98:101], v[60:63]
	v_mfma_f32_16x16x32_bf16 v[56:59], v[136:139], v[98:101], v[56:59]
	v_mfma_f32_16x16x32_bf16 v[52:55], v[140:143], v[98:101], v[52:55]
	v_mfma_f32_16x16x32_bf16 v[48:51], v[144:147], v[98:101], v[48:51]
	v_mfma_f32_16x16x32_bf16 v[44:47], v[132:135], v[120:123], v[44:47]
	v_mfma_f32_16x16x32_bf16 v[40:43], v[136:139], v[120:123], v[40:43]
	v_mfma_f32_16x16x32_bf16 v[36:39], v[140:143], v[120:123], v[36:39]
	v_mfma_f32_16x16x32_bf16 v[32:35], v[144:147], v[120:123], v[32:35]
	v_mfma_f32_16x16x32_bf16 v[28:31], v[132:135], v[124:127], v[28:31]
	v_mfma_f32_16x16x32_bf16 v[24:27], v[136:139], v[124:127], v[24:27]
	v_mfma_f32_16x16x32_bf16 v[20:23], v[140:143], v[124:127], v[20:23]
	v_mfma_f32_16x16x32_bf16 v[16:19], v[144:147], v[124:127], v[16:19]
	v_mfma_f32_16x16x32_bf16 v[12:15], v[132:135], v[128:131], v[12:15]
	v_mfma_f32_16x16x32_bf16 v[8:11], v[136:139], v[128:131], v[8:11]
	v_mfma_f32_16x16x32_bf16 v[4:7], v[140:143], v[128:131], v[4:7]
	v_mfma_f32_16x16x32_bf16 v[0:3], v[144:147], v[128:131], v[0:3]
	s_setprio 0
	v_add_u32_e32 v102, v102, v97
	ds_read_b128 v[98:101], v102
	ds_read_b128 v[120:123], v102 offset:2048
	ds_read_b128 v[124:127], v102 offset:4096
	ds_read_b128 v[128:131], v102 offset:6144
	v_add_u32_e32 v102, v103, v97
	ds_read_b128 v[132:135], v102 offset:32768
	ds_read_b128 v[136:139], v102 offset:34816
	ds_read_b128 v[140:143], v102 offset:36864
	ds_read_b128 v[144:147], v102 offset:38912
	s_setprio 1
	s_waitcnt lgkmcnt(0)
	v_mfma_f32_16x16x32_bf16 v[60:63], v[132:135], v[98:101], v[60:63]
	v_mfma_f32_16x16x32_bf16 v[56:59], v[136:139], v[98:101], v[56:59]
	v_mfma_f32_16x16x32_bf16 v[52:55], v[140:143], v[98:101], v[52:55]
	v_mfma_f32_16x16x32_bf16 v[48:51], v[144:147], v[98:101], v[48:51]
	v_mfma_f32_16x16x32_bf16 v[44:47], v[132:135], v[120:123], v[44:47]
	v_mfma_f32_16x16x32_bf16 v[40:43], v[136:139], v[120:123], v[40:43]
	v_mfma_f32_16x16x32_bf16 v[36:39], v[140:143], v[120:123], v[36:39]
	v_mfma_f32_16x16x32_bf16 v[32:35], v[144:147], v[120:123], v[32:35]
	v_mfma_f32_16x16x32_bf16 v[28:31], v[132:135], v[124:127], v[28:31]
	v_mfma_f32_16x16x32_bf16 v[24:27], v[136:139], v[124:127], v[24:27]
	v_mfma_f32_16x16x32_bf16 v[20:23], v[140:143], v[124:127], v[20:23]
	v_mfma_f32_16x16x32_bf16 v[16:19], v[144:147], v[124:127], v[16:19]
	v_mfma_f32_16x16x32_bf16 v[12:15], v[132:135], v[128:131], v[12:15]
	v_mfma_f32_16x16x32_bf16 v[8:11], v[136:139], v[128:131], v[8:11]
	v_mfma_f32_16x16x32_bf16 v[4:7], v[140:143], v[128:131], v[4:7]
	v_mfma_f32_16x16x32_bf16 v[0:3], v[144:147], v[128:131], v[0:3]
	s_setprio 0
	s_waitcnt vmcnt(0)
	s_add_u32 s36, s36, 0x80
	s_addc_u32 s37, s37, 0
	s_addk_i32 s0, 0x2000
	s_cmpk_lg_i32 s36, 0x780
	s_waitcnt vmcnt(0)
	s_barrier
	s_cbranch_scc1 .LBB0_882
	ds_read_b128 v[86:89], v92 offset:16384
	ds_read_b128 v[98:101], v92 offset:18432
	ds_read_b128 v[120:123], v92 offset:20480
	ds_read_b128 v[124:127], v92 offset:22528
	ds_read_b128 v[128:131], v93 offset:49152
	ds_read_b128 v[132:135], v93 offset:51200
	ds_read_b128 v[136:139], v93 offset:53248
	ds_read_b128 v[140:143], v93 offset:55296
	s_setprio 1
	s_waitcnt lgkmcnt(3)
	v_mfma_f32_16x16x32_bf16 v[60:63], v[128:131], v[86:89], v[60:63]
	s_waitcnt lgkmcnt(2)
	v_mfma_f32_16x16x32_bf16 v[56:59], v[132:135], v[86:89], v[56:59]
	s_waitcnt lgkmcnt(1)
	v_mfma_f32_16x16x32_bf16 v[52:55], v[136:139], v[86:89], v[52:55]
	s_waitcnt lgkmcnt(0)
	v_mfma_f32_16x16x32_bf16 v[48:51], v[140:143], v[86:89], v[48:51]
	v_mfma_f32_16x16x32_bf16 v[40:43], v[132:135], v[98:101], v[40:43]
	v_mfma_f32_16x16x32_bf16 v[36:39], v[136:139], v[98:101], v[36:39]
	v_mfma_f32_16x16x32_bf16 v[32:35], v[140:143], v[98:101], v[32:35]
	v_mfma_f32_16x16x32_bf16 v[20:23], v[136:139], v[120:123], v[20:23]
	v_mfma_f32_16x16x32_bf16 v[16:19], v[140:143], v[120:123], v[16:19]
	v_mfma_f32_16x16x32_bf16 v[0:3], v[140:143], v[124:127], v[0:3]
	v_mfma_f32_16x16x32_bf16 v[86:89], v[128:131], v[98:101], v[44:47]
	v_mfma_f32_16x16x32_bf16 v[98:101], v[128:131], v[120:123], v[28:31]
	v_mfma_f32_16x16x32_bf16 v[144:147], v[132:135], v[120:123], v[24:27]
	v_mfma_f32_16x16x32_bf16 v[120:123], v[128:131], v[124:127], v[12:15]
	v_mfma_f32_16x16x32_bf16 v[128:131], v[132:135], v[124:127], v[8:11]
	v_mfma_f32_16x16x32_bf16 v[132:135], v[136:139], v[124:127], v[4:7]
	s_setprio 0
	s_nop 1
	ds_read_b128 v[4:7], v94 offset:16384
	ds_read_b128 v[8:11], v94 offset:18432
	ds_read_b128 v[124:127], v94 offset:20480
	ds_read_b128 v[136:139], v94 offset:22528
	ds_read_b128 v[140:143], v95 offset:49152
	ds_read_b128 v[148:151], v95 offset:51200
	ds_read_b128 v[152:155], v95 offset:53248
	ds_read_b128 v[156:159], v95 offset:55296
	s_setprio 1
	s_waitcnt lgkmcnt(3)
	v_mfma_f32_16x16x32_bf16 v[60:63], v[140:143], v[4:7], v[60:63]
	s_waitcnt lgkmcnt(2)
	v_mfma_f32_16x16x32_bf16 v[44:47], v[148:151], v[4:7], v[56:59]
	s_waitcnt lgkmcnt(1)
	v_mfma_f32_16x16x32_bf16 v[28:31], v[152:155], v[4:7], v[52:55]
	s_waitcnt lgkmcnt(0)
	v_mfma_f32_16x16x32_bf16 v[12:15], v[156:159], v[4:7], v[48:51]
	v_mfma_f32_16x16x32_bf16 v[56:59], v[140:143], v[8:11], v[86:89]
	v_mfma_f32_16x16x32_bf16 v[40:43], v[148:151], v[8:11], v[40:43]
	v_mfma_f32_16x16x32_bf16 v[24:27], v[152:155], v[8:11], v[36:39]
	v_mfma_f32_16x16x32_bf16 v[8:11], v[156:159], v[8:11], v[32:35]
	v_mfma_f32_16x16x32_bf16 v[52:55], v[140:143], v[124:127], v[98:101]
	v_mfma_f32_16x16x32_bf16 v[36:39], v[148:151], v[124:127], v[144:147]
	v_mfma_f32_16x16x32_bf16 v[20:23], v[152:155], v[124:127], v[20:23]
	v_mfma_f32_16x16x32_bf16 v[4:7], v[156:159], v[124:127], v[16:19]
	v_mfma_f32_16x16x32_bf16 v[48:51], v[140:143], v[136:139], v[120:123]
	v_mfma_f32_16x16x32_bf16 v[32:35], v[148:151], v[136:139], v[128:131]
	v_mfma_f32_16x16x32_bf16 v[16:19], v[152:155], v[136:139], v[132:135]
	v_mfma_f32_16x16x32_bf16 v[0:3], v[156:159], v[136:139], v[0:3]
	s_setprio 0
	s_waitcnt vmcnt(0)
	s_cmpk_gt_i32 s1, 0x7f
	s_barrier
	s_cbranch_scc0 .LBB0_885
	s_add_i32 s0, s24, 0xffffc000
	s_lshr_b32 s0, s0, 8
	v_readlane_b32 s6, v180, 24
	s_add_i32 s6, s0, s6
	s_and_b32 s10, s24, 0x80
	s_lshl_b64 s[8:9], s[6:7], 8
	v_readlane_b32 s36, v182, 19
	s_or_b32 s8, s8, s10
	s_mov_b64 s[10:11], 0
	v_readlane_b32 s37, v182, 20
	s_branch .LBB0_886

.LBB0_895:
	s_setprio 3
	s_and_b32 s0, s10, 0x2000
	s_xor_b32 s1, s0, 0x2000
	s_lshl_b32 s101, s1, 1
	s_add_u32 s101, s101, s100
	s_add_u32 m0, s101, 0x0
	s_nop 0
	global_load_lds_dwordx4 v[184:185], off
	s_add_u32 m0, s101, 0x1000
	v_lshl_add_u64 v[184:185], v[184:185], 0, vcc
	global_load_lds_dwordx4 v[186:187], off
	s_add_u32 m0, s101, 0x2000
	v_lshl_add_u64 v[186:187], v[186:187], 0, vcc
	global_load_lds_dwordx4 v[188:189], off
	s_add_u32 m0, s101, 0x3000
	v_lshl_add_u64 v[188:189], v[188:189], 0, vcc
	global_load_lds_dwordx4 v[190:191], off
	s_add_u32 m0, s101, 0x8000
	v_lshl_add_u64 v[190:191], v[190:191], 0, vcc
	global_load_lds_dwordx4 v[192:193], off
	s_add_u32 m0, s101, 0x9000
	v_lshl_add_u64 v[192:193], v[192:193], 0, vcc
	global_load_lds_dwordx4 v[194:195], off
	s_add_u32 m0, s101, 0xa000
	v_lshl_add_u64 v[194:195], v[194:195], 0, vcc
	global_load_lds_dwordx4 v[196:197], off
	s_add_u32 m0, s101, 0xb000
	v_lshl_add_u64 v[196:197], v[196:197], 0, vcc
	global_load_lds_dwordx4 v[198:199], off
	v_lshl_add_u64 v[198:199], v[198:199], 0, vcc
	s_lshl_b32 s0, s0, 1
	v_add_u32_e32 v68, s0, v120
	v_add_u32_e32 v102, s0, v121
	v_add_u32_e32 v98, v68, v133
	v_add_u32_e32 v103, v102, v133
	ds_read_b128 v[86:89], v98
	ds_read_b128 v[90:93], v98 offset:2048
	ds_read_b128 v[94:97], v98 offset:4096
	ds_read_b128 v[98:101], v98 offset:6144
	ds_read_b128 v[144:147], v103 offset:32768
	ds_read_b128 v[148:151], v103 offset:34816
	ds_read_b128 v[152:155], v103 offset:36864
	ds_read_b128 v[156:159], v103 offset:38912
	s_setprio 1
	s_waitcnt lgkmcnt(0)
	v_mfma_f32_16x16x32_bf16 v[60:63], v[86:89], v[144:147], v[60:63]
	v_mfma_f32_16x16x32_bf16 v[56:59], v[86:89], v[148:151], v[56:59]
	v_mfma_f32_16x16x32_bf16 v[52:55], v[86:89], v[152:155], v[52:55]
	v_mfma_f32_16x16x32_bf16 v[48:51], v[86:89], v[156:159], v[48:51]
	v_mfma_f32_16x16x32_bf16 v[44:47], v[90:93], v[144:147], v[44:47]
	v_mfma_f32_16x16x32_bf16 v[40:43], v[90:93], v[148:151], v[40:43]
	v_mfma_f32_16x16x32_bf16 v[36:39], v[90:93], v[152:155], v[36:39]
	v_mfma_f32_16x16x32_bf16 v[32:35], v[90:93], v[156:159], v[32:35]
	v_mfma_f32_16x16x32_bf16 v[28:31], v[94:97], v[144:147], v[28:31]
	v_mfma_f32_16x16x32_bf16 v[24:27], v[94:97], v[148:151], v[24:27]
	v_mfma_f32_16x16x32_bf16 v[20:23], v[94:97], v[152:155], v[20:23]
	v_mfma_f32_16x16x32_bf16 v[16:19], v[94:97], v[156:159], v[16:19]
	v_mfma_f32_16x16x32_bf16 v[12:15], v[98:101], v[144:147], v[12:15]
	v_mfma_f32_16x16x32_bf16 v[8:11], v[98:101], v[148:151], v[8:11]
	v_mfma_f32_16x16x32_bf16 v[4:7], v[98:101], v[152:155], v[4:7]
	v_mfma_f32_16x16x32_bf16 v[0:3], v[98:101], v[156:159], v[0:3]
	s_setprio 0
	v_add_u32_e32 v68, v68, v134
	ds_read_b128 v[86:89], v68
	ds_read_b128 v[90:93], v68 offset:2048
	ds_read_b128 v[94:97], v68 offset:4096
	ds_read_b128 v[98:101], v68 offset:6144
	v_add_u32_e32 v68, v102, v134
	ds_read_b128 v[144:147], v68 offset:32768
	ds_read_b128 v[148:151], v68 offset:34816
	ds_read_b128 v[152:155], v68 offset:36864
	ds_read_b128 v[156:159], v68 offset:38912
	s_setprio 1
	s_waitcnt lgkmcnt(0)
	v_mfma_f32_16x16x32_bf16 v[60:63], v[86:89], v[144:147], v[60:63]
	v_mfma_f32_16x16x32_bf16 v[56:59], v[86:89], v[148:151], v[56:59]
	v_mfma_f32_16x16x32_bf16 v[52:55], v[86:89], v[152:155], v[52:55]
	v_mfma_f32_16x16x32_bf16 v[48:51], v[86:89], v[156:159], v[48:51]
	v_mfma_f32_16x16x32_bf16 v[44:47], v[90:93], v[144:147], v[44:47]
	v_mfma_f32_16x16x32_bf16 v[40:43], v[90:93], v[148:151], v[40:43]
	v_mfma_f32_16x16x32_bf16 v[36:39], v[90:93], v[152:155], v[36:39]
	v_mfma_f32_16x16x32_bf16 v[32:35], v[90:93], v[156:159], v[32:35]
	v_mfma_f32_16x16x32_bf16 v[28:31], v[94:97], v[144:147], v[28:31]
	v_mfma_f32_16x16x32_bf16 v[24:27], v[94:97], v[148:151], v[24:27]
	v_mfma_f32_16x16x32_bf16 v[20:23], v[94:97], v[152:155], v[20:23]
	v_mfma_f32_16x16x32_bf16 v[16:19], v[94:97], v[156:159], v[16:19]
	v_mfma_f32_16x16x32_bf16 v[12:15], v[98:101], v[144:147], v[12:15]
	v_mfma_f32_16x16x32_bf16 v[8:11], v[98:101], v[148:151], v[8:11]
	v_mfma_f32_16x16x32_bf16 v[4:7], v[98:101], v[152:155], v[4:7]
	v_mfma_f32_16x16x32_bf16 v[0:3], v[98:101], v[156:159], v[0:3]
	s_setprio 0
	s_addk_i32 s10, 0x2000
	s_waitcnt vmcnt(0)
	s_add_u32 s36, s36, 0x80
	s_addc_u32 s37, s37, 0
	s_cmpk_lg_i32 s36, 0x780
	s_waitcnt vmcnt(0)
	s_barrier
	s_cbranch_scc1 .LBB0_895
	ds_read_b128 v[82:85], v122 offset:55296
	ds_read_b128 v[86:89], v122 offset:53248
	ds_read_b128 v[90:93], v122 offset:51200
	ds_read_b128 v[94:97], v122 offset:49152
	ds_read_b128 v[98:101], v123 offset:22528
	ds_read_b128 v[144:147], v123 offset:20480
	ds_read_b128 v[148:151], v123 offset:18432
	ds_read_b128 v[152:155], v123 offset:16384
	s_setprio 1
	s_waitcnt lgkmcnt(0)
	v_mfma_f32_16x16x32_bf16 v[60:63], v[152:155], v[94:97], v[60:63]
	v_mfma_f32_16x16x32_bf16 v[52:55], v[152:155], v[86:89], v[52:55]
	v_mfma_f32_16x16x32_bf16 v[48:51], v[152:155], v[82:85], v[48:51]
	v_mfma_f32_16x16x32_bf16 v[44:47], v[148:151], v[94:97], v[44:47]
	v_mfma_f32_16x16x32_bf16 v[40:43], v[148:151], v[90:93], v[40:43]
	v_mfma_f32_16x16x32_bf16 v[36:39], v[148:151], v[86:89], v[36:39]
	v_mfma_f32_16x16x32_bf16 v[32:35], v[148:151], v[82:85], v[32:35]
	v_mfma_f32_16x16x32_bf16 v[4:7], v[98:101], v[86:89], v[4:7]
	v_mfma_f32_16x16x32_bf16 v[156:159], v[152:155], v[90:93], v[56:59]
	v_mfma_f32_16x16x32_bf16 v[148:151], v[144:147], v[94:97], v[28:31]
	v_mfma_f32_16x16x32_bf16 v[152:155], v[144:147], v[90:93], v[24:27]
	v_mfma_f32_16x16x32_bf16 v[160:163], v[144:147], v[86:89], v[20:23]
	v_mfma_f32_16x16x32_bf16 v[144:147], v[144:147], v[82:85], v[16:19]
	v_mfma_f32_16x16x32_bf16 v[94:97], v[98:101], v[94:97], v[12:15]
	v_mfma_f32_16x16x32_bf16 v[90:93], v[98:101], v[90:93], v[8:11]
	v_mfma_f32_16x16x32_bf16 v[82:85], v[98:101], v[82:85], v[0:3]
	s_setprio 0
	s_nop 1
	ds_read_b128 v[0:3], v124 offset:16384
	ds_read_b128 v[8:11], v124 offset:18432
	ds_read_b128 v[12:15], v124 offset:20480
	ds_read_b128 v[86:89], v124 offset:22528
	ds_read_b128 v[98:101], v125 offset:49152
	ds_read_b128 v[164:167], v125 offset:51200
	ds_read_b128 v[168:171], v125 offset:53248
	ds_read_b128 v[172:175], v125 offset:55296
	s_setprio 1
	s_waitcnt lgkmcnt(3)
	v_mfma_f32_16x16x32_bf16 v[56:59], v[0:3], v[98:101], v[60:63]
	s_waitcnt lgkmcnt(2)
	v_mfma_f32_16x16x32_bf16 v[60:63], v[0:3], v[164:167], v[156:159]
	s_waitcnt lgkmcnt(1)
	v_mfma_f32_16x16x32_bf16 v[24:27], v[0:3], v[168:171], v[52:55]
	s_waitcnt lgkmcnt(0)
	v_mfma_f32_16x16x32_bf16 v[28:31], v[0:3], v[172:175], v[48:51]
	v_mfma_f32_16x16x32_bf16 v[52:55], v[8:11], v[98:101], v[44:47]
	v_mfma_f32_16x16x32_bf16 v[48:51], v[8:11], v[164:167], v[40:43]
	v_mfma_f32_16x16x32_bf16 v[16:19], v[8:11], v[168:171], v[36:39]
	v_mfma_f32_16x16x32_bf16 v[20:23], v[8:11], v[172:175], v[32:35]
	v_mfma_f32_16x16x32_bf16 v[40:43], v[12:15], v[98:101], v[148:151]
	v_mfma_f32_16x16x32_bf16 v[44:47], v[12:15], v[164:167], v[152:155]
	v_mfma_f32_16x16x32_bf16 v[8:11], v[12:15], v[168:171], v[160:163]
	v_mfma_f32_16x16x32_bf16 v[12:15], v[12:15], v[172:175], v[144:147]
	v_mfma_f32_16x16x32_bf16 v[32:35], v[86:89], v[98:101], v[94:97]
	v_mfma_f32_16x16x32_bf16 v[36:39], v[86:89], v[164:167], v[90:93]
	v_mfma_f32_16x16x32_bf16 v[0:3], v[86:89], v[168:171], v[4:7]
	v_mfma_f32_16x16x32_bf16 v[4:7], v[86:89], v[172:175], v[82:85]
	s_setprio 0
	s_waitcnt vmcnt(0)
	s_cmpk_lt_i32 s9, 0x80
	s_cselect_b64 s[42:43], -1, 0
	s_cmpk_gt_i32 s9, 0x7f
	s_mov_b64 s[0:1], -1
	s_barrier
	s_cbranch_scc0 .LBB0_904
	s_and_b32 s10, s20, 0x80
	s_cbranch_execz .LBB0_905

.LBB0_1239:
	s_setprio 3
	s_and_b32 s9, s8, 0x2000
	s_xor_b32 s18, s9, 0x2000
	s_lshl_b32 s101, s18, 1
	s_add_u32 s101, s101, s100
	s_add_u32 m0, s101, 0x0
	s_nop 0
	global_load_lds_dwordx4 v[184:185], off
	s_add_u32 m0, s101, 0x1000
	v_lshl_add_u64 v[184:185], v[184:185], 0, vcc
	global_load_lds_dwordx4 v[186:187], off
	s_add_u32 m0, s101, 0x2000
	v_lshl_add_u64 v[186:187], v[186:187], 0, vcc
	global_load_lds_dwordx4 v[188:189], off
	s_add_u32 m0, s101, 0x3000
	v_lshl_add_u64 v[188:189], v[188:189], 0, vcc
	global_load_lds_dwordx4 v[190:191], off
	s_add_u32 m0, s101, 0x8000
	v_lshl_add_u64 v[190:191], v[190:191], 0, vcc
	global_load_lds_dwordx4 v[192:193], off
	s_add_u32 m0, s101, 0x9000
	v_lshl_add_u64 v[192:193], v[192:193], 0, vcc
	global_load_lds_dwordx4 v[194:195], off
	s_add_u32 m0, s101, 0xa000
	v_lshl_add_u64 v[194:195], v[194:195], 0, vcc
	global_load_lds_dwordx4 v[196:197], off
	s_add_u32 m0, s101, 0xb000
	v_lshl_add_u64 v[196:197], v[196:197], 0, vcc
	global_load_lds_dwordx4 v[198:199], off
	v_lshl_add_u64 v[198:199], v[198:199], 0, vcc
	s_lshl_b32 s9, s9, 1
	v_add_u32_e32 v136, s9, v84
	v_add_u32_e32 v137, s9, v83
	v_add_u32_e32 v100, v136, v86
	v_add_u32_e32 v132, v137, v86
	ds_read_b128 v[88:91], v100
	ds_read_b128 v[92:95], v100 offset:2048
	ds_read_b128 v[96:99], v100 offset:4096
	ds_read_b128 v[100:103], v100 offset:6144
	ds_read_b128 v[120:123], v132 offset:32768
	ds_read_b128 v[124:127], v132 offset:34816
	ds_read_b128 v[128:131], v132 offset:36864
	ds_read_b128 v[132:135], v132 offset:38912
	s_setprio 1
	s_waitcnt lgkmcnt(0)
	v_mfma_f32_16x16x32_bf16 v[60:63], v[120:123], v[88:91], v[60:63]
	v_mfma_f32_16x16x32_bf16 v[56:59], v[124:127], v[88:91], v[56:59]
	v_mfma_f32_16x16x32_bf16 v[52:55], v[128:131], v[88:91], v[52:55]
	v_mfma_f32_16x16x32_bf16 v[48:51], v[132:135], v[88:91], v[48:51]
	v_mfma_f32_16x16x32_bf16 v[44:47], v[120:123], v[92:95], v[44:47]
	v_mfma_f32_16x16x32_bf16 v[40:43], v[124:127], v[92:95], v[40:43]
	v_mfma_f32_16x16x32_bf16 v[36:39], v[128:131], v[92:95], v[36:39]
	v_mfma_f32_16x16x32_bf16 v[32:35], v[132:135], v[92:95], v[32:35]
	v_mfma_f32_16x16x32_bf16 v[28:31], v[120:123], v[96:99], v[28:31]
	v_mfma_f32_16x16x32_bf16 v[24:27], v[124:127], v[96:99], v[24:27]
	v_mfma_f32_16x16x32_bf16 v[20:23], v[128:131], v[96:99], v[20:23]
	v_mfma_f32_16x16x32_bf16 v[16:19], v[132:135], v[96:99], v[16:19]
	v_mfma_f32_16x16x32_bf16 v[12:15], v[120:123], v[100:103], v[12:15]
	v_mfma_f32_16x16x32_bf16 v[8:11], v[124:127], v[100:103], v[8:11]
	v_mfma_f32_16x16x32_bf16 v[4:7], v[128:131], v[100:103], v[4:7]
	v_mfma_f32_16x16x32_bf16 v[0:3], v[132:135], v[100:103], v[0:3]
	s_setprio 0
	v_add_u32_e32 v100, v136, v87
	v_add_u32_e32 v132, v137, v87
	ds_read_b128 v[88:91], v100
	ds_read_b128 v[92:95], v100 offset:2048
	ds_read_b128 v[96:99], v100 offset:4096
	ds_read_b128 v[100:103], v100 offset:6144
	ds_read_b128 v[120:123], v132 offset:32768
	ds_read_b128 v[124:127], v132 offset:34816
	ds_read_b128 v[128:131], v132 offset:36864
	ds_read_b128 v[132:135], v132 offset:38912
	s_setprio 1
	s_waitcnt lgkmcnt(0)
	v_mfma_f32_16x16x32_bf16 v[60:63], v[120:123], v[88:91], v[60:63]
	v_mfma_f32_16x16x32_bf16 v[56:59], v[124:127], v[88:91], v[56:59]
	v_mfma_f32_16x16x32_bf16 v[52:55], v[128:131], v[88:91], v[52:55]
	v_mfma_f32_16x16x32_bf16 v[48:51], v[132:135], v[88:91], v[48:51]
	v_mfma_f32_16x16x32_bf16 v[44:47], v[120:123], v[92:95], v[44:47]
	v_mfma_f32_16x16x32_bf16 v[40:43], v[124:127], v[92:95], v[40:43]
	v_mfma_f32_16x16x32_bf16 v[36:39], v[128:131], v[92:95], v[36:39]
	v_mfma_f32_16x16x32_bf16 v[32:35], v[132:135], v[92:95], v[32:35]
	v_mfma_f32_16x16x32_bf16 v[28:31], v[120:123], v[96:99], v[28:31]
	v_mfma_f32_16x16x32_bf16 v[24:27], v[124:127], v[96:99], v[24:27]
	v_mfma_f32_16x16x32_bf16 v[20:23], v[128:131], v[96:99], v[20:23]
	v_mfma_f32_16x16x32_bf16 v[16:19], v[132:135], v[96:99], v[16:19]
	v_mfma_f32_16x16x32_bf16 v[12:15], v[120:123], v[100:103], v[12:15]
	v_mfma_f32_16x16x32_bf16 v[8:11], v[124:127], v[100:103], v[8:11]
	v_mfma_f32_16x16x32_bf16 v[4:7], v[128:131], v[100:103], v[4:7]
	v_mfma_f32_16x16x32_bf16 v[0:3], v[132:135], v[100:103], v[0:3]
	s_setprio 0
	s_waitcnt vmcnt(0)
	s_add_u32 s20, s20, 0x80
	s_addc_u32 s21, s21, 0
	s_addk_i32 s8, 0x2000
	s_cmp_lg_u32 s1, s20
	s_waitcnt vmcnt(0)
	s_barrier
	s_cbranch_scc1 .LBB0_1239
	s_lshl_b32 s1, s36, 14
	s_addk_i32 s1, 0x4000
	s_and_b32 s1, s1, 0x4000
	v_add_u32_e32 v132, s1, v84
	v_add_u32_e32 v133, s1, v83
	v_add_u32_e32 v96, v132, v86
	v_add_u32_e32 v128, v133, v86
	ds_read_b128 v[78:81], v96
	ds_read_b128 v[88:91], v96 offset:2048
	ds_read_b128 v[92:95], v96 offset:4096
	ds_read_b128 v[96:99], v96 offset:6144
	ds_read_b128 v[100:103], v128 offset:32768
	ds_read_b128 v[120:123], v128 offset:34816
	ds_read_b128 v[124:127], v128 offset:36864
	ds_read_b128 v[128:131], v128 offset:38912
	s_setprio 1
	s_waitcnt lgkmcnt(3)
	v_mfma_f32_16x16x32_bf16 v[60:63], v[100:103], v[78:81], v[60:63]
	s_waitcnt lgkmcnt(2)
	v_mfma_f32_16x16x32_bf16 v[56:59], v[120:123], v[78:81], v[56:59]
	s_waitcnt lgkmcnt(1)
	v_mfma_f32_16x16x32_bf16 v[52:55], v[124:127], v[78:81], v[52:55]
	s_waitcnt lgkmcnt(0)
	v_mfma_f32_16x16x32_bf16 v[48:51], v[128:131], v[78:81], v[48:51]
	v_mfma_f32_16x16x32_bf16 v[44:47], v[100:103], v[88:91], v[44:47]
	v_mfma_f32_16x16x32_bf16 v[40:43], v[120:123], v[88:91], v[40:43]
	v_mfma_f32_16x16x32_bf16 v[36:39], v[124:127], v[88:91], v[36:39]
	v_mfma_f32_16x16x32_bf16 v[32:35], v[128:131], v[88:91], v[32:35]
	v_mfma_f32_16x16x32_bf16 v[28:31], v[100:103], v[92:95], v[28:31]
	v_mfma_f32_16x16x32_bf16 v[24:27], v[120:123], v[92:95], v[24:27]
	v_mfma_f32_16x16x32_bf16 v[20:23], v[124:127], v[92:95], v[20:23]
	v_mfma_f32_16x16x32_bf16 v[16:19], v[128:131], v[92:95], v[16:19]
	v_mfma_f32_16x16x32_bf16 v[12:15], v[100:103], v[96:99], v[12:15]
	v_mfma_f32_16x16x32_bf16 v[8:11], v[120:123], v[96:99], v[8:11]
	v_mfma_f32_16x16x32_bf16 v[4:7], v[124:127], v[96:99], v[4:7]
	v_mfma_f32_16x16x32_bf16 v[0:3], v[128:131], v[96:99], v[0:3]
	s_setprio 0
	v_add_u32_e32 v96, v132, v87
	v_add_u32_e32 v128, v133, v87
	ds_read_b128 v[78:81], v96
	ds_read_b128 v[88:91], v96 offset:2048
	ds_read_b128 v[92:95], v96 offset:4096
	ds_read_b128 v[96:99], v96 offset:6144
	ds_read_b128 v[100:103], v128 offset:32768
	ds_read_b128 v[120:123], v128 offset:34816
	ds_read_b128 v[124:127], v128 offset:36864
	ds_read_b128 v[128:131], v128 offset:38912
	s_setprio 1
	s_waitcnt lgkmcnt(3)
	v_mfma_f32_16x16x32_bf16 v[60:63], v[100:103], v[78:81], v[60:63]
	s_waitcnt lgkmcnt(2)
	v_mfma_f32_16x16x32_bf16 v[56:59], v[120:123], v[78:81], v[56:59]
	s_waitcnt lgkmcnt(1)
	v_mfma_f32_16x16x32_bf16 v[52:55], v[124:127], v[78:81], v[52:55]
	s_waitcnt lgkmcnt(0)
	v_mfma_f32_16x16x32_bf16 v[48:51], v[128:131], v[78:81], v[48:51]
	v_mfma_f32_16x16x32_bf16 v[44:47], v[100:103], v[88:91], v[44:47]
	v_mfma_f32_16x16x32_bf16 v[40:43], v[120:123], v[88:91], v[40:43]
	v_mfma_f32_16x16x32_bf16 v[36:39], v[124:127], v[88:91], v[36:39]
	v_mfma_f32_16x16x32_bf16 v[32:35], v[128:131], v[88:91], v[32:35]
	v_mfma_f32_16x16x32_bf16 v[28:31], v[100:103], v[92:95], v[28:31]
	v_mfma_f32_16x16x32_bf16 v[24:27], v[120:123], v[92:95], v[24:27]
	v_mfma_f32_16x16x32_bf16 v[20:23], v[124:127], v[92:95], v[20:23]
	v_mfma_f32_16x16x32_bf16 v[16:19], v[128:131], v[92:95], v[16:19]
	v_mfma_f32_16x16x32_bf16 v[12:15], v[100:103], v[96:99], v[12:15]
	v_mfma_f32_16x16x32_bf16 v[8:11], v[120:123], v[96:99], v[8:11]
	v_mfma_f32_16x16x32_bf16 v[4:7], v[124:127], v[96:99], v[4:7]
	v_mfma_f32_16x16x32_bf16 v[0:3], v[128:131], v[96:99], v[0:3]
	s_setprio 0
	s_lshl_b32 s1, s25, 3
	s_lshl_b32 s8, s11, 1
	s_or_b32 s1, s8, s1
	s_or_b32 s1, s1, s13
	s_lshl_b32 s1, s1, 4
	s_or_b32 s8, s1, s24
	s_ashr_i32 s9, s8, 31
	s_lshl_b64 s[8:9], s[8:9], 18
	s_add_u32 s8, s52, s8
	v_add_lshl_u32 v78, s10, v71, 8
	s_addc_u32 s9, s53, s9
	v_or_b32_e32 v80, s0, v85
	v_ashrrev_i32_e32 v79, 31, v78
	v_lshl_add_u64 v[78:79], v[78:79], 1, s[8:9]
	v_cvt_pk_bf16_f32 v60, v60, v61
	v_cvt_pk_bf16_f32 v61, v62, v63
	v_lshlrev_b32_e32 v62, 1, v80
	v_mov_b32_e32 v63, v69
	v_lshl_add_u64 v[80:81], v[78:79], 0, v[62:63]
	v_cvt_pk_bf16_f32 v48, v48, v49
	v_cvt_pk_bf16_f32 v49, v50, v51
	s_mov_b64 s[0:1], 0x2000
	s_waitcnt vmcnt(0)
	s_barrier
	global_store_dwordx2 v[80:81], v[48:49], off offset:96
	v_lshl_add_u64 v[48:49], v[78:79], 0, s[0:1]
	v_cvt_pk_bf16_f32 v44, v44, v45
	v_cvt_pk_bf16_f32 v45, v46, v47
	v_lshl_add_u64 v[46:47], v[48:49], 0, v[62:63]
	v_cvt_pk_bf16_f32 v40, v40, v41
	v_cvt_pk_bf16_f32 v41, v42, v43
	v_or_b32_e32 v42, 32, v62
	v_mov_b32_e32 v43, v69
	global_store_dwordx2 v[46:47], v[44:45], off
	v_lshl_add_u64 v[44:45], v[48:49], 0, v[42:43]
	v_cvt_pk_bf16_f32 v36, v36, v37
	v_cvt_pk_bf16_f32 v37, v38, v39
	v_or_b32_e32 v38, 64, v62
	v_mov_b32_e32 v39, v69
	global_store_dwordx2 v[44:45], v[40:41], off
	v_lshl_add_u64 v[40:41], v[48:49], 0, v[38:39]
	v_cvt_pk_bf16_f32 v32, v32, v33
	v_cvt_pk_bf16_f32 v33, v34, v35
	v_or_b32_e32 v34, 0x60, v62
	v_mov_b32_e32 v35, v69
	global_store_dwordx2 v[40:41], v[36:37], off
	v_lshl_add_u64 v[36:37], v[48:49], 0, v[34:35]
	s_mov_b64 s[0:1], 0x4000
	global_store_dwordx2 v[36:37], v[32:33], off
	v_lshl_add_u64 v[32:33], v[78:79], 0, s[0:1]
	v_cvt_pk_bf16_f32 v16, v16, v17
	v_cvt_pk_bf16_f32 v17, v18, v19
	v_lshl_add_u64 v[18:19], v[32:33], 0, v[34:35]
	s_mov_b64 s[0:1], 0x6000
	global_store_dwordx2 v[18:19], v[16:17], off
	v_lshl_add_u64 v[16:17], v[78:79], 0, s[0:1]
	v_readlane_b32 s0, v181, 50
	s_add_i32 s6, s6, s84
	s_add_i32 s12, s12, s0
	v_cvt_pk_bf16_f32 v56, v56, v57
	v_cvt_pk_bf16_f32 v57, v58, v59
	v_cvt_pk_bf16_f32 v52, v52, v53
	v_cvt_pk_bf16_f32 v53, v54, v55
	v_cvt_pk_bf16_f32 v28, v28, v29
	v_cvt_pk_bf16_f32 v29, v30, v31
	v_lshl_add_u64 v[30:31], v[32:33], 0, v[62:63]
	v_cvt_pk_bf16_f32 v24, v24, v25
	v_cvt_pk_bf16_f32 v25, v26, v27
	v_lshl_add_u64 v[26:27], v[32:33], 0, v[42:43]
	v_cvt_pk_bf16_f32 v20, v20, v21
	v_cvt_pk_bf16_f32 v21, v22, v23
	v_lshl_add_u64 v[22:23], v[32:33], 0, v[38:39]
	v_cvt_pk_bf16_f32 v12, v12, v13
	v_cvt_pk_bf16_f32 v13, v14, v15
	v_lshl_add_u64 v[14:15], v[16:17], 0, v[62:63]
	v_cvt_pk_bf16_f32 v8, v8, v9
	v_cvt_pk_bf16_f32 v9, v10, v11
	v_lshl_add_u64 v[10:11], v[16:17], 0, v[42:43]
	v_cvt_pk_bf16_f32 v4, v4, v5
	v_cvt_pk_bf16_f32 v5, v6, v7
	v_lshl_add_u64 v[6:7], v[16:17], 0, v[38:39]
	v_cvt_pk_bf16_f32 v0, v0, v1
	v_cvt_pk_bf16_f32 v1, v2, v3
	v_lshl_add_u64 v[2:3], v[16:17], 0, v[34:35]
	s_cmpk_lt_i32 s6, 0x800
	global_store_dwordx2 v[80:81], v[60:61], off
	global_store_dwordx2 v[80:81], v[56:57], off offset:32
	global_store_dwordx2 v[80:81], v[52:53], off offset:64
	global_store_dwordx2 v[30:31], v[28:29], off
	global_store_dwordx2 v[26:27], v[24:25], off
	global_store_dwordx2 v[22:23], v[20:21], off
	global_store_dwordx2 v[14:15], v[12:13], off
	global_store_dwordx2 v[10:11], v[8:9], off
	global_store_dwordx2 v[6:7], v[4:5], off
	global_store_dwordx2 v[2:3], v[0:1], off
	s_cbranch_scc1 .LBB0_1234
	v_readlane_b32 s50, v180, 0
	s_mov_b32 s18, 0x42ce8ed0
	s_mov_b32 s19, 0xc2b17218
	s_mov_b32 s48, s5
	v_readlane_b32 s51, v180, 1

.LBB0_1487:
	s_setprio 3
	s_and_b32 s6, s0, 0x2000
	s_xor_b32 s8, s6, 0x2000
	s_lshl_b32 s101, s8, 1
	s_add_u32 s101, s101, s100
	s_add_u32 m0, s101, 0x0
	s_nop 0
	global_load_lds_dwordx4 v[184:185], off
	s_add_u32 m0, s101, 0x1000
	v_lshl_add_u64 v[184:185], v[184:185], 0, vcc
	global_load_lds_dwordx4 v[186:187], off
	s_add_u32 m0, s101, 0x2000
	v_lshl_add_u64 v[186:187], v[186:187], 0, vcc
	global_load_lds_dwordx4 v[188:189], off
	s_add_u32 m0, s101, 0x3000
	v_lshl_add_u64 v[188:189], v[188:189], 0, vcc
	global_load_lds_dwordx4 v[190:191], off
	s_add_u32 m0, s101, 0x8000
	v_lshl_add_u64 v[190:191], v[190:191], 0, vcc
	global_load_lds_dwordx4 v[192:193], off
	s_add_u32 m0, s101, 0x9000
	v_lshl_add_u64 v[192:193], v[192:193], 0, vcc
	global_load_lds_dwordx4 v[194:195], off
	s_add_u32 m0, s101, 0xa000
	v_lshl_add_u64 v[194:195], v[194:195], 0, vcc
	global_load_lds_dwordx4 v[196:197], off
	s_add_u32 m0, s101, 0xb000
	v_lshl_add_u64 v[196:197], v[196:197], 0, vcc
	global_load_lds_dwordx4 v[198:199], off
	v_lshl_add_u64 v[198:199], v[198:199], 0, vcc
	s_lshl_b32 s6, s6, 1
	v_add_u32_e32 v148, s6, v92
	v_add_u32_e32 v149, s6, v71
	v_add_u32_e32 v128, v148, v98
	v_add_u32_e32 v144, v149, v98
	ds_read_b128 v[100:103], v128
	ds_read_b128 v[120:123], v128 offset:2048
	ds_read_b128 v[124:127], v128 offset:4096
	ds_read_b128 v[128:131], v128 offset:6144
	ds_read_b128 v[132:135], v144 offset:32768
	ds_read_b128 v[136:139], v144 offset:34816
	ds_read_b128 v[140:143], v144 offset:36864
	ds_read_b128 v[144:147], v144 offset:38912
	s_setprio 1
	s_waitcnt lgkmcnt(0)
	v_mfma_f32_16x16x32_bf16 v[60:63], v[132:135], v[100:103], v[60:63]
	v_mfma_f32_16x16x32_bf16 v[56:59], v[136:139], v[100:103], v[56:59]
	v_mfma_f32_16x16x32_bf16 v[52:55], v[140:143], v[100:103], v[52:55]
	v_mfma_f32_16x16x32_bf16 v[48:51], v[144:147], v[100:103], v[48:51]
	v_mfma_f32_16x16x32_bf16 v[44:47], v[132:135], v[120:123], v[44:47]
	v_mfma_f32_16x16x32_bf16 v[40:43], v[136:139], v[120:123], v[40:43]
	v_mfma_f32_16x16x32_bf16 v[36:39], v[140:143], v[120:123], v[36:39]
	v_mfma_f32_16x16x32_bf16 v[32:35], v[144:147], v[120:123], v[32:35]
	v_mfma_f32_16x16x32_bf16 v[28:31], v[132:135], v[124:127], v[28:31]
	v_mfma_f32_16x16x32_bf16 v[24:27], v[136:139], v[124:127], v[24:27]
	v_mfma_f32_16x16x32_bf16 v[20:23], v[140:143], v[124:127], v[20:23]
	v_mfma_f32_16x16x32_bf16 v[16:19], v[144:147], v[124:127], v[16:19]
	v_mfma_f32_16x16x32_bf16 v[12:15], v[132:135], v[128:131], v[12:15]
	v_mfma_f32_16x16x32_bf16 v[8:11], v[136:139], v[128:131], v[8:11]
	v_mfma_f32_16x16x32_bf16 v[4:7], v[140:143], v[128:131], v[4:7]
	v_mfma_f32_16x16x32_bf16 v[0:3], v[144:147], v[128:131], v[0:3]
	s_setprio 0
	v_add_u32_e32 v128, v148, v99
	v_add_u32_e32 v144, v149, v99
	ds_read_b128 v[100:103], v128
	ds_read_b128 v[120:123], v128 offset:2048
	ds_read_b128 v[124:127], v128 offset:4096
	ds_read_b128 v[128:131], v128 offset:6144
	ds_read_b128 v[132:135], v144 offset:32768
	ds_read_b128 v[136:139], v144 offset:34816
	ds_read_b128 v[140:143], v144 offset:36864
	ds_read_b128 v[144:147], v144 offset:38912
	s_setprio 1
	s_waitcnt lgkmcnt(0)
	v_mfma_f32_16x16x32_bf16 v[60:63], v[132:135], v[100:103], v[60:63]
	v_mfma_f32_16x16x32_bf16 v[56:59], v[136:139], v[100:103], v[56:59]
	v_mfma_f32_16x16x32_bf16 v[52:55], v[140:143], v[100:103], v[52:55]
	v_mfma_f32_16x16x32_bf16 v[48:51], v[144:147], v[100:103], v[48:51]
	v_mfma_f32_16x16x32_bf16 v[44:47], v[132:135], v[120:123], v[44:47]
	v_mfma_f32_16x16x32_bf16 v[40:43], v[136:139], v[120:123], v[40:43]
	v_mfma_f32_16x16x32_bf16 v[36:39], v[140:143], v[120:123], v[36:39]
	v_mfma_f32_16x16x32_bf16 v[32:35], v[144:147], v[120:123], v[32:35]
	v_mfma_f32_16x16x32_bf16 v[28:31], v[132:135], v[124:127], v[28:31]
	v_mfma_f32_16x16x32_bf16 v[24:27], v[136:139], v[124:127], v[24:27]
	v_mfma_f32_16x16x32_bf16 v[20:23], v[140:143], v[124:127], v[20:23]
	v_mfma_f32_16x16x32_bf16 v[16:19], v[144:147], v[124:127], v[16:19]
	v_mfma_f32_16x16x32_bf16 v[12:15], v[132:135], v[128:131], v[12:15]
	v_mfma_f32_16x16x32_bf16 v[8:11], v[136:139], v[128:131], v[8:11]
	v_mfma_f32_16x16x32_bf16 v[4:7], v[140:143], v[128:131], v[4:7]
	v_mfma_f32_16x16x32_bf16 v[0:3], v[144:147], v[128:131], v[0:3]
	s_setprio 0
	s_waitcnt vmcnt(0)
	s_add_u32 s36, s36, 0x80
	s_addc_u32 s37, s37, 0
	s_addk_i32 s0, 0x2000
	s_cmpk_lg_i32 s36, 0xf80
	s_waitcnt vmcnt(0)
	s_barrier
	s_cbranch_scc1 .LBB0_1487
	ds_read_b128 v[88:91], v94 offset:16384
	ds_read_b128 v[100:103], v94 offset:18432
	ds_read_b128 v[120:123], v94 offset:20480
	ds_read_b128 v[124:127], v94 offset:22528
	ds_read_b128 v[128:131], v95 offset:49152
	ds_read_b128 v[132:135], v95 offset:51200
	ds_read_b128 v[136:139], v95 offset:53248
	ds_read_b128 v[140:143], v95 offset:55296
	s_setprio 1
	s_waitcnt lgkmcnt(3)
	v_mfma_f32_16x16x32_bf16 v[60:63], v[128:131], v[88:91], v[60:63]
	s_waitcnt lgkmcnt(2)
	v_mfma_f32_16x16x32_bf16 v[56:59], v[132:135], v[88:91], v[56:59]
	s_waitcnt lgkmcnt(1)
	v_mfma_f32_16x16x32_bf16 v[52:55], v[136:139], v[88:91], v[52:55]
	s_waitcnt lgkmcnt(0)
	v_mfma_f32_16x16x32_bf16 v[48:51], v[140:143], v[88:91], v[48:51]
	v_mfma_f32_16x16x32_bf16 v[40:43], v[132:135], v[100:103], v[40:43]
	v_mfma_f32_16x16x32_bf16 v[36:39], v[136:139], v[100:103], v[36:39]
	v_mfma_f32_16x16x32_bf16 v[32:35], v[140:143], v[100:103], v[32:35]
	v_mfma_f32_16x16x32_bf16 v[20:23], v[136:139], v[120:123], v[20:23]
	v_mfma_f32_16x16x32_bf16 v[16:19], v[140:143], v[120:123], v[16:19]
	v_mfma_f32_16x16x32_bf16 v[0:3], v[140:143], v[124:127], v[0:3]
	v_mfma_f32_16x16x32_bf16 v[88:91], v[128:131], v[100:103], v[44:47]
	v_mfma_f32_16x16x32_bf16 v[100:103], v[128:131], v[120:123], v[28:31]
	v_mfma_f32_16x16x32_bf16 v[144:147], v[132:135], v[120:123], v[24:27]
	v_mfma_f32_16x16x32_bf16 v[120:123], v[128:131], v[124:127], v[12:15]
	v_mfma_f32_16x16x32_bf16 v[128:131], v[132:135], v[124:127], v[8:11]
	v_mfma_f32_16x16x32_bf16 v[132:135], v[136:139], v[124:127], v[4:7]
	s_setprio 0
	s_nop 1
	ds_read_b128 v[4:7], v96 offset:16384
	ds_read_b128 v[8:11], v96 offset:18432
	ds_read_b128 v[124:127], v96 offset:20480
	ds_read_b128 v[136:139], v96 offset:22528
	ds_read_b128 v[140:143], v97 offset:49152
	ds_read_b128 v[148:151], v97 offset:51200
	ds_read_b128 v[152:155], v97 offset:53248
	ds_read_b128 v[156:159], v97 offset:55296
	s_setprio 1
	s_waitcnt lgkmcnt(3)
	v_mfma_f32_16x16x32_bf16 v[60:63], v[140:143], v[4:7], v[60:63]
	s_waitcnt lgkmcnt(2)
	v_mfma_f32_16x16x32_bf16 v[44:47], v[148:151], v[4:7], v[56:59]
	s_waitcnt lgkmcnt(1)
	v_mfma_f32_16x16x32_bf16 v[28:31], v[152:155], v[4:7], v[52:55]
	s_waitcnt lgkmcnt(0)
	v_mfma_f32_16x16x32_bf16 v[12:15], v[156:159], v[4:7], v[48:51]
	v_mfma_f32_16x16x32_bf16 v[56:59], v[140:143], v[8:11], v[88:91]
	v_mfma_f32_16x16x32_bf16 v[40:43], v[148:151], v[8:11], v[40:43]
	v_mfma_f32_16x16x32_bf16 v[24:27], v[152:155], v[8:11], v[36:39]
	v_mfma_f32_16x16x32_bf16 v[8:11], v[156:159], v[8:11], v[32:35]
	v_mfma_f32_16x16x32_bf16 v[52:55], v[140:143], v[124:127], v[100:103]
	v_mfma_f32_16x16x32_bf16 v[36:39], v[148:151], v[124:127], v[144:147]
	v_mfma_f32_16x16x32_bf16 v[20:23], v[152:155], v[124:127], v[20:23]
	v_mfma_f32_16x16x32_bf16 v[4:7], v[156:159], v[124:127], v[16:19]
	v_mfma_f32_16x16x32_bf16 v[48:51], v[140:143], v[136:139], v[120:123]
	v_mfma_f32_16x16x32_bf16 v[32:35], v[148:151], v[136:139], v[128:131]
	v_mfma_f32_16x16x32_bf16 v[16:19], v[152:155], v[136:139], v[132:135]
	v_mfma_f32_16x16x32_bf16 v[0:3], v[156:159], v[136:139], v[0:3]
	s_setprio 0
	s_waitcnt vmcnt(0)
	s_cmpk_gt_i32 s1, 0x7f
	s_barrier
	s_cbranch_scc0 .LBB0_1490
	s_add_i32 s0, s24, 0xffffc000
	s_lshr_b32 s0, s0, 8
	v_readlane_b32 s6, v180, 24
	s_add_i32 s6, s0, s6
	s_and_b32 s10, s24, 0x80
	s_lshl_b64 s[8:9], s[6:7], 8
	v_readlane_b32 s36, v182, 19
	s_or_b32 s8, s8, s10
	s_mov_b64 s[10:11], 0
	v_readlane_b32 s37, v182, 20
	s_branch .LBB0_1491

.LBB0_1498:
	s_setprio 3
	s_and_b32 s10, s6, 0x2000
	s_xor_b32 s8, s10, 0x2000
	s_lshl_b32 s101, s8, 1
	s_add_u32 s101, s101, s100
	s_add_u32 m0, s101, 0x0
	s_nop 0
	global_load_lds_dwordx4 v[184:185], off
	s_add_u32 m0, s101, 0x1000
	v_lshl_add_u64 v[184:185], v[184:185], 0, vcc
	global_load_lds_dwordx4 v[186:187], off
	s_add_u32 m0, s101, 0x2000
	v_lshl_add_u64 v[186:187], v[186:187], 0, vcc
	global_load_lds_dwordx4 v[188:189], off
	s_add_u32 m0, s101, 0x3000
	v_lshl_add_u64 v[188:189], v[188:189], 0, vcc
	global_load_lds_dwordx4 v[190:191], off
	s_add_u32 m0, s101, 0x8000
	v_lshl_add_u64 v[190:191], v[190:191], 0, vcc
	global_load_lds_dwordx4 v[192:193], off
	s_add_u32 m0, s101, 0x9000
	v_lshl_add_u64 v[192:193], v[192:193], 0, vcc
	global_load_lds_dwordx4 v[194:195], off
	s_add_u32 m0, s101, 0xa000
	v_lshl_add_u64 v[194:195], v[194:195], 0, vcc
	global_load_lds_dwordx4 v[196:197], off
	s_add_u32 m0, s101, 0xb000
	v_lshl_add_u64 v[196:197], v[196:197], 0, vcc
	global_load_lds_dwordx4 v[198:199], off
	v_lshl_add_u64 v[198:199], v[198:199], 0, vcc
	s_lshl_b32 s8, s10, 1
	v_add_u32_e32 v68, s8, v84
	v_add_u32_e32 v140, s8, v83
	v_add_u32_e32 v120, v68, v90
	v_add_u32_e32 v136, v140, v90
	ds_read_b128 v[92:95], v120
	ds_read_b128 v[96:99], v120 offset:2048
	ds_read_b128 v[100:103], v120 offset:4096
	ds_read_b128 v[120:123], v120 offset:6144
	ds_read_b128 v[124:127], v136 offset:32768
	ds_read_b128 v[128:131], v136 offset:34816
	ds_read_b128 v[132:135], v136 offset:36864
	ds_read_b128 v[136:139], v136 offset:38912
	s_setprio 1
	s_waitcnt lgkmcnt(0)
	v_mfma_f32_16x16x32_bf16 v[60:63], v[124:127], v[92:95], v[60:63]
	v_mfma_f32_16x16x32_bf16 v[56:59], v[128:131], v[92:95], v[56:59]
	v_mfma_f32_16x16x32_bf16 v[52:55], v[132:135], v[92:95], v[52:55]
	v_mfma_f32_16x16x32_bf16 v[48:51], v[136:139], v[92:95], v[48:51]
	v_mfma_f32_16x16x32_bf16 v[44:47], v[124:127], v[96:99], v[44:47]
	v_mfma_f32_16x16x32_bf16 v[40:43], v[128:131], v[96:99], v[40:43]
	v_mfma_f32_16x16x32_bf16 v[36:39], v[132:135], v[96:99], v[36:39]
	v_mfma_f32_16x16x32_bf16 v[32:35], v[136:139], v[96:99], v[32:35]
	v_mfma_f32_16x16x32_bf16 v[28:31], v[124:127], v[100:103], v[28:31]
	v_mfma_f32_16x16x32_bf16 v[24:27], v[128:131], v[100:103], v[24:27]
	v_mfma_f32_16x16x32_bf16 v[20:23], v[132:135], v[100:103], v[20:23]
	v_mfma_f32_16x16x32_bf16 v[16:19], v[136:139], v[100:103], v[16:19]
	v_mfma_f32_16x16x32_bf16 v[12:15], v[124:127], v[120:123], v[12:15]
	v_mfma_f32_16x16x32_bf16 v[8:11], v[128:131], v[120:123], v[8:11]
	v_mfma_f32_16x16x32_bf16 v[4:7], v[132:135], v[120:123], v[4:7]
	v_mfma_f32_16x16x32_bf16 v[0:3], v[136:139], v[120:123], v[0:3]
	s_setprio 0
	v_add_u32_e32 v68, v68, v91
	ds_read_b128 v[92:95], v68
	ds_read_b128 v[96:99], v68 offset:2048
	ds_read_b128 v[100:103], v68 offset:4096
	ds_read_b128 v[120:123], v68 offset:6144
	v_add_u32_e32 v68, v140, v91
	ds_read_b128 v[124:127], v68 offset:32768
	ds_read_b128 v[128:131], v68 offset:34816
	ds_read_b128 v[132:135], v68 offset:36864
	ds_read_b128 v[136:139], v68 offset:38912
	s_setprio 1
	s_waitcnt lgkmcnt(0)
	v_mfma_f32_16x16x32_bf16 v[60:63], v[124:127], v[92:95], v[60:63]
	v_mfma_f32_16x16x32_bf16 v[56:59], v[128:131], v[92:95], v[56:59]
	v_mfma_f32_16x16x32_bf16 v[52:55], v[132:135], v[92:95], v[52:55]
	v_mfma_f32_16x16x32_bf16 v[48:51], v[136:139], v[92:95], v[48:51]
	v_mfma_f32_16x16x32_bf16 v[44:47], v[124:127], v[96:99], v[44:47]
	v_mfma_f32_16x16x32_bf16 v[40:43], v[128:131], v[96:99], v[40:43]
	v_mfma_f32_16x16x32_bf16 v[36:39], v[132:135], v[96:99], v[36:39]
	v_mfma_f32_16x16x32_bf16 v[32:35], v[136:139], v[96:99], v[32:35]
	v_mfma_f32_16x16x32_bf16 v[28:31], v[124:127], v[100:103], v[28:31]
	v_mfma_f32_16x16x32_bf16 v[24:27], v[128:131], v[100:103], v[24:27]
	v_mfma_f32_16x16x32_bf16 v[20:23], v[132:135], v[100:103], v[20:23]
	v_mfma_f32_16x16x32_bf16 v[16:19], v[136:139], v[100:103], v[16:19]
	v_mfma_f32_16x16x32_bf16 v[12:15], v[124:127], v[120:123], v[12:15]
	v_mfma_f32_16x16x32_bf16 v[8:11], v[128:131], v[120:123], v[8:11]
	v_mfma_f32_16x16x32_bf16 v[4:7], v[132:135], v[120:123], v[4:7]
	v_mfma_f32_16x16x32_bf16 v[0:3], v[136:139], v[120:123], v[0:3]
	s_setprio 0
	s_addk_i32 s6, 0x2000
	s_waitcnt vmcnt(0)
	s_add_u32 s36, s36, 0x80
	s_addc_u32 s37, s37, 0
	s_cmpk_lg_i32 s36, 0x780
	s_waitcnt vmcnt(0)
	s_barrier
	s_cbranch_scc1 .LBB0_1498
	ds_read_b128 v[78:81], v85 offset:55296
	ds_read_b128 v[92:95], v85 offset:53248
	ds_read_b128 v[96:99], v85 offset:51200
	ds_read_b128 v[100:103], v85 offset:49152
	ds_read_b128 v[120:123], v86 offset:22528
	ds_read_b128 v[124:127], v86 offset:20480
	ds_read_b128 v[128:131], v86 offset:18432
	ds_read_b128 v[132:135], v86 offset:16384
	s_setprio 1
	s_waitcnt lgkmcnt(0)
	v_mfma_f32_16x16x32_bf16 v[60:63], v[100:103], v[132:135], v[60:63]
	v_mfma_f32_16x16x32_bf16 v[56:59], v[96:99], v[132:135], v[56:59]
	v_mfma_f32_16x16x32_bf16 v[52:55], v[92:95], v[132:135], v[52:55]
	v_mfma_f32_16x16x32_bf16 v[48:51], v[78:81], v[132:135], v[48:51]
	v_mfma_f32_16x16x32_bf16 v[44:47], v[100:103], v[128:131], v[44:47]
	v_mfma_f32_16x16x32_bf16 v[40:43], v[96:99], v[128:131], v[40:43]
	v_mfma_f32_16x16x32_bf16 v[36:39], v[92:95], v[128:131], v[36:39]
	v_mfma_f32_16x16x32_bf16 v[32:35], v[78:81], v[128:131], v[32:35]
	v_mfma_f32_16x16x32_bf16 v[28:31], v[100:103], v[124:127], v[28:31]
	v_mfma_f32_16x16x32_bf16 v[24:27], v[96:99], v[124:127], v[24:27]
	v_mfma_f32_16x16x32_bf16 v[20:23], v[92:95], v[124:127], v[20:23]
	v_mfma_f32_16x16x32_bf16 v[16:19], v[78:81], v[124:127], v[16:19]
	v_mfma_f32_16x16x32_bf16 v[12:15], v[100:103], v[120:123], v[12:15]
	v_mfma_f32_16x16x32_bf16 v[8:11], v[96:99], v[120:123], v[8:11]
	v_mfma_f32_16x16x32_bf16 v[4:7], v[92:95], v[120:123], v[4:7]
	v_mfma_f32_16x16x32_bf16 v[0:3], v[78:81], v[120:123], v[0:3]
	s_setprio 0
	ds_read_b128 v[78:81], v87 offset:16384
	ds_read_b128 v[92:95], v87 offset:18432
	ds_read_b128 v[96:99], v87 offset:20480
	ds_read_b128 v[100:103], v87 offset:22528
	ds_read_b128 v[120:123], v88 offset:49152
	ds_read_b128 v[124:127], v88 offset:51200
	ds_read_b128 v[128:131], v88 offset:53248
	ds_read_b128 v[132:135], v88 offset:55296
	s_setprio 1
	s_waitcnt lgkmcnt(3)
	v_mfma_f32_16x16x32_bf16 v[60:63], v[120:123], v[78:81], v[60:63]
	s_waitcnt lgkmcnt(2)
	v_mfma_f32_16x16x32_bf16 v[56:59], v[124:127], v[78:81], v[56:59]
	s_waitcnt lgkmcnt(1)
	v_mfma_f32_16x16x32_bf16 v[52:55], v[128:131], v[78:81], v[52:55]
	s_waitcnt lgkmcnt(0)
	v_mfma_f32_16x16x32_bf16 v[48:51], v[132:135], v[78:81], v[48:51]
	v_mfma_f32_16x16x32_bf16 v[44:47], v[120:123], v[92:95], v[44:47]
	v_mfma_f32_16x16x32_bf16 v[40:43], v[124:127], v[92:95], v[40:43]
	v_mfma_f32_16x16x32_bf16 v[36:39], v[128:131], v[92:95], v[36:39]
	v_mfma_f32_16x16x32_bf16 v[32:35], v[132:135], v[92:95], v[32:35]
	v_mfma_f32_16x16x32_bf16 v[28:31], v[120:123], v[96:99], v[28:31]
	v_mfma_f32_16x16x32_bf16 v[24:27], v[124:127], v[96:99], v[24:27]
	v_mfma_f32_16x16x32_bf16 v[20:23], v[128:131], v[96:99], v[20:23]
	v_mfma_f32_16x16x32_bf16 v[16:19], v[132:135], v[96:99], v[16:19]
	v_mfma_f32_16x16x32_bf16 v[12:15], v[120:123], v[100:103], v[12:15]
	v_mfma_f32_16x16x32_bf16 v[8:11], v[124:127], v[100:103], v[8:11]
	v_mfma_f32_16x16x32_bf16 v[4:7], v[128:131], v[100:103], v[4:7]
	v_mfma_f32_16x16x32_bf16 v[0:3], v[132:135], v[100:103], v[0:3]
	s_setprio 0
	s_ashr_i32 s1, s1, 4
	s_mul_hi_i32 s6, s1, 0x4200000
	s_mul_i32 s1, s1, 0x4200000
	s_add_u32 s8, s90, s1
	v_add_u32_e32 v78, s20, v71
	s_addc_u32 s9, s91, s6
	s_and_b32 s1, s24, 0x780
	v_ashrrev_i32_e32 v79, 31, v78
	v_or_b32_e32 v68, s1, v89
	v_lshlrev_b64 v[80:81], 12, v[78:79]
	v_lshl_add_u64 v[80:81], s[8:9], 0, v[80:81]
	v_lshlrev_b32_e32 v68, 1, v68
	v_cvt_pk_bf16_f32 v60, v60, v61
	v_cvt_pk_bf16_f32 v61, v62, v63
	v_lshl_add_u64 v[62:63], v[80:81], 0, v[68:69]
	v_cvt_pk_bf16_f32 v48, v48, v49
	v_cvt_pk_bf16_f32 v49, v50, v51
	s_waitcnt vmcnt(0)
	s_barrier
	global_store_dwordx2 v[62:63], v[48:49], off offset:96
	v_or_b32_e32 v48, 16, v78
	v_ashrrev_i32_e32 v49, 31, v48
	v_lshlrev_b64 v[48:49], 12, v[48:49]
	v_lshl_add_u64 v[48:49], s[8:9], 0, v[48:49]
	v_cvt_pk_bf16_f32 v44, v44, v45
	v_cvt_pk_bf16_f32 v45, v46, v47
	v_lshl_add_u64 v[46:47], v[48:49], 0, v[68:69]
	v_cvt_pk_bf16_f32 v32, v32, v33
	v_cvt_pk_bf16_f32 v33, v34, v35
	global_store_dwordx2 v[46:47], v[32:33], off offset:96
	v_or_b32_e32 v32, 32, v78
	v_ashrrev_i32_e32 v33, 31, v32
	v_lshlrev_b64 v[32:33], 12, v[32:33]
	v_lshl_add_u64 v[32:33], s[8:9], 0, v[32:33]
	v_cvt_pk_bf16_f32 v28, v28, v29
	v_cvt_pk_bf16_f32 v29, v30, v31
	v_lshl_add_u64 v[30:31], v[32:33], 0, v[68:69]
	v_cvt_pk_bf16_f32 v16, v16, v17
	v_cvt_pk_bf16_f32 v17, v18, v19
	global_store_dwordx2 v[30:31], v[16:17], off offset:96
	v_or_b32_e32 v16, 48, v78
	v_ashrrev_i32_e32 v17, 31, v16
	v_lshlrev_b64 v[16:17], 12, v[16:17]
	v_lshl_add_u64 v[16:17], s[8:9], 0, v[16:17]
	s_add_i32 s0, s0, s84
	v_cvt_pk_bf16_f32 v56, v56, v57
	v_cvt_pk_bf16_f32 v57, v58, v59
	v_cvt_pk_bf16_f32 v52, v52, v53
	v_cvt_pk_bf16_f32 v53, v54, v55
	v_cvt_pk_bf16_f32 v40, v40, v41
	v_cvt_pk_bf16_f32 v41, v42, v43
	v_cvt_pk_bf16_f32 v36, v36, v37
	v_cvt_pk_bf16_f32 v37, v38, v39
	v_cvt_pk_bf16_f32 v24, v24, v25
	v_cvt_pk_bf16_f32 v25, v26, v27
	v_cvt_pk_bf16_f32 v20, v20, v21
	v_cvt_pk_bf16_f32 v21, v22, v23
	v_cvt_pk_bf16_f32 v12, v12, v13
	v_cvt_pk_bf16_f32 v13, v14, v15
	v_lshl_add_u64 v[14:15], v[16:17], 0, v[68:69]
	v_cvt_pk_bf16_f32 v8, v8, v9
	v_cvt_pk_bf16_f32 v9, v10, v11
	v_cvt_pk_bf16_f32 v4, v4, v5
	v_cvt_pk_bf16_f32 v5, v6, v7
	v_cvt_pk_bf16_f32 v0, v0, v1
	v_cvt_pk_bf16_f32 v1, v2, v3
	s_cmpk_lt_i32 s0, 0x18c0
	global_store_dwordx2 v[62:63], v[60:61], off
	global_store_dwordx2 v[62:63], v[56:57], off offset:32
	global_store_dwordx2 v[62:63], v[52:53], off offset:64
	global_store_dwordx2 v[46:47], v[44:45], off
	global_store_dwordx2 v[46:47], v[40:41], off offset:32
	global_store_dwordx2 v[46:47], v[36:37], off offset:64
	global_store_dwordx2 v[30:31], v[28:29], off
	global_store_dwordx2 v[30:31], v[24:25], off offset:32
	global_store_dwordx2 v[30:31], v[20:21], off offset:64
	global_store_dwordx2 v[14:15], v[12:13], off
	global_store_dwordx2 v[14:15], v[8:9], off offset:32
	global_store_dwordx2 v[14:15], v[4:5], off offset:64
	global_store_dwordx2 v[14:15], v[0:1], off offset:96
	s_cbranch_scc1 .LBB0_1497

.LBB0_1707:
	s_setprio 3
	s_and_b32 s6, s0, 0x2000
	s_xor_b32 s8, s6, 0x2000
	s_lshl_b32 s101, s8, 1
	s_add_u32 s101, s101, s100
	s_add_u32 m0, s101, 0x0
	s_nop 0
	global_load_lds_dwordx4 v[184:185], off
	s_add_u32 m0, s101, 0x1000
	v_lshl_add_u64 v[184:185], v[184:185], 0, vcc
	global_load_lds_dwordx4 v[186:187], off
	s_add_u32 m0, s101, 0x2000
	v_lshl_add_u64 v[186:187], v[186:187], 0, vcc
	global_load_lds_dwordx4 v[188:189], off
	s_add_u32 m0, s101, 0x3000
	v_lshl_add_u64 v[188:189], v[188:189], 0, vcc
	global_load_lds_dwordx4 v[190:191], off
	s_add_u32 m0, s101, 0x8000
	v_lshl_add_u64 v[190:191], v[190:191], 0, vcc
	global_load_lds_dwordx4 v[192:193], off
	s_add_u32 m0, s101, 0x9000
	v_lshl_add_u64 v[192:193], v[192:193], 0, vcc
	global_load_lds_dwordx4 v[194:195], off
	s_add_u32 m0, s101, 0xa000
	v_lshl_add_u64 v[194:195], v[194:195], 0, vcc
	global_load_lds_dwordx4 v[196:197], off
	s_add_u32 m0, s101, 0xb000
	v_lshl_add_u64 v[196:197], v[196:197], 0, vcc
	global_load_lds_dwordx4 v[198:199], off
	v_lshl_add_u64 v[198:199], v[198:199], 0, vcc
	s_lshl_b32 s6, s6, 1
	v_add_u32_e32 v102, s6, v90
	v_add_u32_e32 v103, s6, v71
	v_add_u32_e32 v128, v102, v96
	v_add_u32_e32 v144, v103, v96
	ds_read_b128 v[98:101], v128
	ds_read_b128 v[120:123], v128 offset:2048
	ds_read_b128 v[124:127], v128 offset:4096
	ds_read_b128 v[128:131], v128 offset:6144
	ds_read_b128 v[132:135], v144 offset:32768
	ds_read_b128 v[136:139], v144 offset:34816
	ds_read_b128 v[140:143], v144 offset:36864
	ds_read_b128 v[144:147], v144 offset:38912
	s_setprio 1
	s_waitcnt lgkmcnt(0)
	v_mfma_f32_16x16x32_bf16 v[60:63], v[132:135], v[98:101], v[60:63]
	v_mfma_f32_16x16x32_bf16 v[56:59], v[136:139], v[98:101], v[56:59]
	v_mfma_f32_16x16x32_bf16 v[52:55], v[140:143], v[98:101], v[52:55]
	v_mfma_f32_16x16x32_bf16 v[48:51], v[144:147], v[98:101], v[48:51]
	v_mfma_f32_16x16x32_bf16 v[44:47], v[132:135], v[120:123], v[44:47]
	v_mfma_f32_16x16x32_bf16 v[40:43], v[136:139], v[120:123], v[40:43]
	v_mfma_f32_16x16x32_bf16 v[36:39], v[140:143], v[120:123], v[36:39]
	v_mfma_f32_16x16x32_bf16 v[32:35], v[144:147], v[120:123], v[32:35]
	v_mfma_f32_16x16x32_bf16 v[28:31], v[132:135], v[124:127], v[28:31]
	v_mfma_f32_16x16x32_bf16 v[24:27], v[136:139], v[124:127], v[24:27]
	v_mfma_f32_16x16x32_bf16 v[20:23], v[140:143], v[124:127], v[20:23]
	v_mfma_f32_16x16x32_bf16 v[16:19], v[144:147], v[124:127], v[16:19]
	v_mfma_f32_16x16x32_bf16 v[12:15], v[132:135], v[128:131], v[12:15]
	v_mfma_f32_16x16x32_bf16 v[8:11], v[136:139], v[128:131], v[8:11]
	v_mfma_f32_16x16x32_bf16 v[4:7], v[140:143], v[128:131], v[4:7]
	v_mfma_f32_16x16x32_bf16 v[0:3], v[144:147], v[128:131], v[0:3]
	s_setprio 0
	v_add_u32_e32 v102, v102, v97
	ds_read_b128 v[98:101], v102
	ds_read_b128 v[120:123], v102 offset:2048
	ds_read_b128 v[124:127], v102 offset:4096
	ds_read_b128 v[128:131], v102 offset:6144
	v_add_u32_e32 v102, v103, v97
	ds_read_b128 v[132:135], v102 offset:32768
	ds_read_b128 v[136:139], v102 offset:34816
	ds_read_b128 v[140:143], v102 offset:36864
	ds_read_b128 v[144:147], v102 offset:38912
	s_setprio 1
	s_waitcnt lgkmcnt(0)
	v_mfma_f32_16x16x32_bf16 v[60:63], v[132:135], v[98:101], v[60:63]
	v_mfma_f32_16x16x32_bf16 v[56:59], v[136:139], v[98:101], v[56:59]
	v_mfma_f32_16x16x32_bf16 v[52:55], v[140:143], v[98:101], v[52:55]
	v_mfma_f32_16x16x32_bf16 v[48:51], v[144:147], v[98:101], v[48:51]
	v_mfma_f32_16x16x32_bf16 v[44:47], v[132:135], v[120:123], v[44:47]
	v_mfma_f32_16x16x32_bf16 v[40:43], v[136:139], v[120:123], v[40:43]
	v_mfma_f32_16x16x32_bf16 v[36:39], v[140:143], v[120:123], v[36:39]
	v_mfma_f32_16x16x32_bf16 v[32:35], v[144:147], v[120:123], v[32:35]
	v_mfma_f32_16x16x32_bf16 v[28:31], v[132:135], v[124:127], v[28:31]
	v_mfma_f32_16x16x32_bf16 v[24:27], v[136:139], v[124:127], v[24:27]
	v_mfma_f32_16x16x32_bf16 v[20:23], v[140:143], v[124:127], v[20:23]
	v_mfma_f32_16x16x32_bf16 v[16:19], v[144:147], v[124:127], v[16:19]
	v_mfma_f32_16x16x32_bf16 v[12:15], v[132:135], v[128:131], v[12:15]
	v_mfma_f32_16x16x32_bf16 v[8:11], v[136:139], v[128:131], v[8:11]
	v_mfma_f32_16x16x32_bf16 v[4:7], v[140:143], v[128:131], v[4:7]
	v_mfma_f32_16x16x32_bf16 v[0:3], v[144:147], v[128:131], v[0:3]
	s_setprio 0
	s_waitcnt vmcnt(0)
	s_add_u32 s36, s36, 0x80
	s_addc_u32 s37, s37, 0
	s_addk_i32 s0, 0x2000
	s_cmpk_lg_i32 s36, 0xf80
	s_waitcnt vmcnt(0)
	s_barrier
	s_cbranch_scc1 .LBB0_1707
	ds_read_b128 v[86:89], v92 offset:16384
	ds_read_b128 v[98:101], v92 offset:18432
	ds_read_b128 v[120:123], v92 offset:20480
	ds_read_b128 v[124:127], v92 offset:22528
	ds_read_b128 v[128:131], v93 offset:49152
	ds_read_b128 v[132:135], v93 offset:51200
	ds_read_b128 v[136:139], v93 offset:53248
	ds_read_b128 v[140:143], v93 offset:55296
	s_setprio 1
	s_waitcnt lgkmcnt(3)
	v_mfma_f32_16x16x32_bf16 v[60:63], v[128:131], v[86:89], v[60:63]
	s_waitcnt lgkmcnt(2)
	v_mfma_f32_16x16x32_bf16 v[56:59], v[132:135], v[86:89], v[56:59]
	s_waitcnt lgkmcnt(1)
	v_mfma_f32_16x16x32_bf16 v[52:55], v[136:139], v[86:89], v[52:55]
	s_waitcnt lgkmcnt(0)
	v_mfma_f32_16x16x32_bf16 v[48:51], v[140:143], v[86:89], v[48:51]
	v_mfma_f32_16x16x32_bf16 v[40:43], v[132:135], v[98:101], v[40:43]
	v_mfma_f32_16x16x32_bf16 v[36:39], v[136:139], v[98:101], v[36:39]
	v_mfma_f32_16x16x32_bf16 v[32:35], v[140:143], v[98:101], v[32:35]
	v_mfma_f32_16x16x32_bf16 v[20:23], v[136:139], v[120:123], v[20:23]
	v_mfma_f32_16x16x32_bf16 v[16:19], v[140:143], v[120:123], v[16:19]
	v_mfma_f32_16x16x32_bf16 v[0:3], v[140:143], v[124:127], v[0:3]
	v_mfma_f32_16x16x32_bf16 v[86:89], v[128:131], v[98:101], v[44:47]
	v_mfma_f32_16x16x32_bf16 v[98:101], v[128:131], v[120:123], v[28:31]
	v_mfma_f32_16x16x32_bf16 v[144:147], v[132:135], v[120:123], v[24:27]
	v_mfma_f32_16x16x32_bf16 v[120:123], v[128:131], v[124:127], v[12:15]
	v_mfma_f32_16x16x32_bf16 v[128:131], v[132:135], v[124:127], v[8:11]
	v_mfma_f32_16x16x32_bf16 v[132:135], v[136:139], v[124:127], v[4:7]
	s_setprio 0
	s_nop 1
	ds_read_b128 v[4:7], v94 offset:16384
	ds_read_b128 v[8:11], v94 offset:18432
	ds_read_b128 v[124:127], v94 offset:20480
	ds_read_b128 v[136:139], v94 offset:22528
	ds_read_b128 v[140:143], v95 offset:49152
	ds_read_b128 v[148:151], v95 offset:51200
	ds_read_b128 v[152:155], v95 offset:53248
	ds_read_b128 v[156:159], v95 offset:55296
	s_setprio 1
	s_waitcnt lgkmcnt(3)
	v_mfma_f32_16x16x32_bf16 v[60:63], v[140:143], v[4:7], v[60:63]
	s_waitcnt lgkmcnt(2)
	v_mfma_f32_16x16x32_bf16 v[44:47], v[148:151], v[4:7], v[56:59]
	s_waitcnt lgkmcnt(1)
	v_mfma_f32_16x16x32_bf16 v[28:31], v[152:155], v[4:7], v[52:55]
	s_waitcnt lgkmcnt(0)
	v_mfma_f32_16x16x32_bf16 v[12:15], v[156:159], v[4:7], v[48:51]
	v_mfma_f32_16x16x32_bf16 v[56:59], v[140:143], v[8:11], v[86:89]
	v_mfma_f32_16x16x32_bf16 v[40:43], v[148:151], v[8:11], v[40:43]
	v_mfma_f32_16x16x32_bf16 v[24:27], v[152:155], v[8:11], v[36:39]
	v_mfma_f32_16x16x32_bf16 v[8:11], v[156:159], v[8:11], v[32:35]
	v_mfma_f32_16x16x32_bf16 v[52:55], v[140:143], v[124:127], v[98:101]
	v_mfma_f32_16x16x32_bf16 v[36:39], v[148:151], v[124:127], v[144:147]
	v_mfma_f32_16x16x32_bf16 v[20:23], v[152:155], v[124:127], v[20:23]
	v_mfma_f32_16x16x32_bf16 v[4:7], v[156:159], v[124:127], v[16:19]
	v_mfma_f32_16x16x32_bf16 v[48:51], v[140:143], v[136:139], v[120:123]
	v_mfma_f32_16x16x32_bf16 v[32:35], v[148:151], v[136:139], v[128:131]
	v_mfma_f32_16x16x32_bf16 v[16:19], v[152:155], v[136:139], v[132:135]
	v_mfma_f32_16x16x32_bf16 v[0:3], v[156:159], v[136:139], v[0:3]
	s_setprio 0
	s_waitcnt vmcnt(0)
	s_cmpk_gt_i32 s1, 0x7f
	s_barrier
	s_cbranch_scc0 .LBB0_1710
	s_add_i32 s0, s24, 0xffffc000
	s_lshr_b32 s0, s0, 8
	v_readlane_b32 s6, v180, 24
	s_add_i32 s6, s0, s6
	s_and_b32 s10, s24, 0x80
	s_lshl_b64 s[8:9], s[6:7], 8
	v_readlane_b32 s36, v182, 19
	s_or_b32 s8, s8, s10
	s_mov_b64 s[10:11], 0
	v_readlane_b32 s37, v182, 20
	s_branch .LBB0_1711
